# stack14 + static s_setprio 1 for the second wave half (waves 4-7) during the attention phase
# speedup vs baseline: 1.0016x; 1.0016x over previous
.LBB0_722:
	s_cmp_lg_u64 s[2:3], 0
	s_cbranch_scc1 .Lprio_skip
	s_setprio 1

.LBB0_893:
	s_setprio 0
	s_load_dwordx2 s[92:93], s[0:1], 0xc8
	v_readlane_b32 s94, v226, 4
	v_readlane_b32 s4, v226, 2
	v_mov_b32_e32 v1, v139
	v_readlane_b32 s95, v226, 5
	v_readlane_b32 s96, v226, 6
	v_readlane_b32 s97, v226, 7
	v_readlane_b32 s5, v226, 3
